# grid barrier: non-leader workgroups invalidate only their L1 (buffer_inv sc0); the per-XCD L2 invalidate is done once by the XCD leader and completes before it releases them
# speedup vs baseline: 1.0112x; 1.0104x over previous
.LBB0_183:
	s_or_b64 exec, exec, s[8:9]
	s_waitcnt vmcnt(0)
	buffer_inv sc0
	s_waitcnt vmcnt(0)

.LBB0_201:
	s_or_b64 exec, exec, s[6:7]
	s_mov_b64 s[6:7], exec
	v_mbcnt_lo_u32_b32 v0, s6, 0
	v_mbcnt_hi_u32_b32 v0, s7, v0
	v_cmp_eq_u32_e32 vcc, 0, v0
	s_waitcnt vmcnt(0)
	buffer_inv sc1
	s_waitcnt vmcnt(0)
	s_and_saveexec_b64 s[8:9], vcc
	s_cbranch_execz .LBB0_203
	s_bcnt1_i32_b64 s0, s[6:7]
	v_mov_b32_e32 v0, s0
	v_readlane_b32 s0, v254, 31
	v_readlane_b32 s1, v254, 32
	s_nop 4
	global_atomic_add v131, v0, s[0:1]

.LBB0_1566:
	s_or_b64 exec, exec, s[6:7]
	s_mov_b64 s[6:7], exec
	v_mbcnt_lo_u32_b32 v0, s6, 0
	v_mbcnt_hi_u32_b32 v0, s7, v0
	v_cmp_eq_u32_e32 vcc, 0, v0
	s_waitcnt vmcnt(0)
	buffer_inv sc1
	s_waitcnt vmcnt(0)
	s_and_saveexec_b64 s[8:9], vcc
	s_cbranch_execnz .LBB0_1567
	s_getpc_b64 s[98:99]
